# residual epilogue: the four gate-vector loads of a unit issued together
# speedup vs baseline: 1.0100x; 1.0040x over previous
;     __device__ __forceinline__ void operator()(const f32x4 (&acc)[2][2][4][2], const Unit& u, int wr, int wc, int fr, int fq) const {
;         const bool lat = u.pm < 64; const int mr = lat ? (u.pm >> 3) : 8;
;         const float* sp = lat ? srclat : srcctx; float* dp = lat ? dstlat : dstctx;
;         const int col0 = u.pn * 256 + wc * 32 + 8 * fq;
;         const size_t off0 = (size_t)((lat ? u.pm : u.pm - 64) * 256 + wr * 64 + fr) * DM + col0;
;         sp += off0; dp += off0;
;         const float* gp = gate + (size_t)mr * 9216 + col0;
;         f32x4 gv[2][2];
; #pragma unroll
;         for (int bj = 0; bj < 2; ++bj)
; #pragma unroll
;             for (int n = 0; n < 2; ++n) gv[bj][n] = *(const f32x4*)(gp + bj * 128 + n * 4) * scale;
.LBB0_854:
	s_lshl_b32 s52, s52, 8
	s_add_i32 s59, s52, 0xffffc000
	s_and_b64 s[82:83], s[82:83], exec
	s_cselect_b32 s52, s52, s59
	s_lshl_b64 s[76:77], s[76:77], 2
	v_lshl_or_b32 v136, s62, 8, v164
	s_add_u32 s76, s75, s76
	v_ashrrev_i32_e32 v137, 31, v136
	s_addc_u32 s77, s78, s77
	v_lshl_add_u64 v[170:171], v[136:137], 2, s[76:77]
	global_load_dwordx4 v[148:151], v[170:171], off offset:16
	global_load_dwordx4 v[152:155], v[170:171], off
	global_load_dwordx4 v[202:205], v[170:171], off offset:528
	global_load_dwordx4 v[208:211], v[170:171], off offset:512
	v_add_u32_e32 v144, s52, v143
	v_ashrrev_i32_e32 v145, 31, v144
	v_lshlrev_b64 v[144:145], 10, v[144:145]
	v_lshl_add_u64 v[144:145], v[144:145], 0, v[136:137]
	v_lshlrev_b64 v[162:163], 2, v[144:145]
	v_lshl_add_u64 v[156:157], s[80:81], 0, v[162:163]
	v_lshl_add_u64 v[162:163], s[48:49], 0, v[162:163]
	s_mov_b64 s[48:49], 0x10000
	s_mov_b32 s52, 0x10000
	s_mov_b32 s0, 0x30000
	s_mov_b32 s61, 0xb0000
	s_waitcnt vmcnt(0)
	v_pk_mul_f32 v[136:137], s[42:43], v[150:151]
	v_pk_mul_f32 v[144:145], s[2:3], v[148:149]
	v_pk_mul_f32 v[158:159], s[42:43], v[154:155]
	v_pk_mul_f32 v[160:161], s[2:3], v[152:153]
	v_pk_mul_f32 v[152:153], s[42:43], v[210:211]
	v_pk_mul_f32 v[154:155], s[2:3], v[208:209]
	v_pk_mul_f32 v[148:149], s[42:43], v[204:205]
	v_pk_mul_f32 v[150:151], s[2:3], v[202:203]
	s_and_b32 s98, s101, 7
	s_cmp_lg_u32 s98, 0
	s_cbranch_scc0 .Lkq_epi_full
	s_and_b32 s98, s101, 7
	s_cmp_eq_u32 s98, 1
	s_cbranch_scc1 .Lkq_epiQ1
	s_and_b32 s98, s101, 7
	s_cmp_eq_u32 s98, 2
	s_cbranch_scc1 .Lkq_epiQ2
	s_and_b32 s98, s101, 7
	s_cmp_eq_u32 s98, 3
	s_cbranch_scc1 .Lkq_epiQ3
	s_branch .Lkq_epiQ4

; __device__ __forceinline__ unsigned xb_ld(unsigned* p)              { return __hip_atomic_load(p, __ATOMIC_RELAXED, __HIP_MEMORY_SCOPE_AGENT); }
; __device__ __forceinline__ void xcd_barrier_complete(unsigned* bar, unsigned x, unsigned& nloc, unsigned& nx) {
;     ...
;         sum = 0u; cnt = 0u; mine = 0u;
; #pragma unroll
;         for (unsigned j = 0; j < 16; ++j) { const unsigned c = xb_ld(&bar[XB_XCNT(j)]); sum += c; cnt += (c > 0u) ? 1u : 0u; mine = (j == x) ? c : mine; }
;         if (sum == G) break;
;         __builtin_amdgcn_s_sleep(1);
;         if ((++sp & 255u) == 0u) { if (xb_ld(&bar[XB_TMO])) break; if (sp > XB_SPIN_CAP) { atomicAdd(&bar[XB_TMO], 1u); break; } }
;     }
.LBB0_971:
	s_cmp_lt_u32 s20, 0x40001
	s_mov_b64 s[16:17], 0
	s_cselect_b64 s[18:19], -1, 0
	s_and_b64 vcc, exec, s[18:19]
	s_cbranch_vccnz .LBB0_968
	s_branch .LBB0_965
	s_nop 0
